# adaLN-RMSNorm row loop v2: one row per step through a 4-buffer ring with three rows of loads in flight (reads and writes interleaved instead of 4-row batches)
# baseline (speedup 1.0000x reference)
; __device__ __forceinline__ void norm_rows(const float* src, int nrows, const float* gam, const float* sc, const float* sh, bf16_t* dst, int tid) {
;   const int lane = tid & 63; const int gw = blockIdx.x * 8 + (tid >> 6), nw = gridDim.x * 8;
; #pragma unroll 1
;   for (int r0 = gw; r0 < nrows; r0 += 4 * nw) {
;     f32x4 v[4][8]; float ss[4]; int rr[4]; bool ok[4];
; #pragma unroll
;     for (int q = 0; q < 4; ++q) { const int r = r0 + q * nw; ok[q] = r < nrows; rr[q] = ok[q] ? r : r0; }
;     ...
;     for (int j = 0; j < 8; ++j) {
;       const int c = 4 * (lane + 64 * j);
;       const f32x4 mul = *(const f32x4*)(gam + c) * (1.0f + *(const f32x4*)(sc + c)); const f32x4 add = *(const f32x4*)(sh + c);
.LBB0_348:
	s_cmp_gt_u32 s84, 10
	v_readlane_b32 s4, v254, 9
	s_cselect_b64 s[8:9], -1, 0
	v_readlane_b32 s5, v254, 10
	s_add_u32 s0, s4, s0
	s_addc_u32 s1, s5, s1
	s_load_dwordx2 s[2:3], s[0:1], 0x0
	s_nop 0
	s_load_dwordx2 s[0:1], s[4:5], 0x110
	s_and_b64 s[4:5], s[8:9], exec
	s_cselect_b32 s4, 0x2000, 0
	v_ashrrev_i32_e32 v145, 6, v146
	s_waitcnt lgkmcnt(0)
	s_add_u32 s2, s2, s4
	s_addc_u32 s3, s3, 0
	v_readlane_b32 s7, v253, 19
	s_cmp_eq_u32 s84, 1
	s_cselect_b64 s[4:5], -1, 0
	v_add_u32_e32 v132, s7, v145
	s_movk_i32 s7, 0x4000
	v_cmp_gt_i32_e32 vcc, s7, v132
	v_ashrrev_i32_e32 v133, 31, v132
	s_and_saveexec_b64 s[14:15], vcc
	s_cbranch_execz .LBB0_399
	s_and_b64 s[10:11], s[4:5], exec
	s_cselect_b32 s7, 0, 0x108
	v_readlane_b32 s10, v254, 9
	v_readlane_b32 s11, v254, 10
	s_add_u32 s10, s10, s7
	s_addc_u32 s11, s11, 0
	s_and_b64 s[8:9], s[8:9], exec
	s_cselect_b32 s7, 0xc000, 0
	s_add_u32 s7, s0, s7
	s_addc_u32 s8, s1, 0
	s_lshl_b32 s6, s6, 2
	s_add_u32 s9, s7, s6
	s_addc_u32 s12, s8, 0
	s_add_u32 s6, s9, 0x6c00000
	s_addc_u32 s7, s12, 0
	v_and_b32_e32 v0, 63, v229
	s_add_u32 s8, s9, 0x6c02000
	v_lshlrev_b32_e32 v138, 4, v0
	v_lshlrev_b32_e32 v0, 3, v0
	v_mov_b32_e32 v1, v139
	s_addc_u32 s9, s12, 0
	v_lshl_add_u64 v[2:3], s[0:1], 0, v[0:1]
	s_mov_b64 s[12:13], 0x6c21000
	v_lshl_add_u64 v[136:137], v[2:3], 0, s[12:13]
	v_or_b32_e32 v2, 0x400, v138
	v_mov_b32_e32 v3, v139
	v_lshl_add_u64 v[154:155], s[8:9], 0, v[2:3]
	v_or_b32_e32 v2, 0x800, v138
	v_lshl_add_u64 v[156:157], s[8:9], 0, v[2:3]
	v_or_b32_e32 v2, 0xc00, v138
	v_lshl_add_u64 v[158:159], s[8:9], 0, v[2:3]
	v_or_b32_e32 v2, 0x1000, v138
	v_lshl_add_u64 v[160:161], s[2:3], 0, v[2:3]
	v_lshl_add_u64 v[162:163], s[8:9], 0, v[2:3]
	v_lshl_add_u64 v[164:165], s[6:7], 0, v[2:3]
	v_or_b32_e32 v2, 0x1400, v138
	v_lshl_add_u64 v[166:167], s[2:3], 0, v[2:3]
	v_lshl_add_u64 v[168:169], s[8:9], 0, v[2:3]
	v_lshl_add_u64 v[170:171], s[6:7], 0, v[2:3]
	v_or_b32_e32 v2, 0x1800, v138
	v_lshl_add_u64 v[172:173], s[2:3], 0, v[2:3]
	v_lshl_add_u64 v[174:175], s[8:9], 0, v[2:3]
	v_lshl_add_u64 v[176:177], s[6:7], 0, v[2:3]
	v_or_b32_e32 v2, 0x1c00, v138
	s_load_dwordx2 s[10:11], s[10:11], 0x0
	v_lshl_add_u64 v[178:179], s[2:3], 0, v[2:3]
	v_lshl_add_u64 v[180:181], s[8:9], 0, v[2:3]
	v_lshl_add_u64 v[182:183], s[6:7], 0, v[2:3]
	v_lshlrev_b64 v[2:3], 12, v[132:133]
	v_or_b32_e32 v2, v2, v0
	v_lshl_add_u64 v[152:153], s[6:7], 0, v[138:139]
	v_lshl_add_u64 v[0:1], s[0:1], 0, v[2:3]
	s_mov_b64 s[6:7], 0x6c21e00
	v_lshl_add_u64 v[184:185], v[0:1], 0, s[6:7]
	v_lshlrev_b64 v[0:1], 13, v[132:133]
	v_or_b32_e32 v0, v0, v138
	s_waitcnt lgkmcnt(0)
	v_lshl_add_u64 v[0:1], s[10:11], 0, v[0:1]
	s_mov_b64 s[6:7], 0x1c00
	v_lshl_add_u64 v[134:135], s[10:11], 0, v[138:139]
	v_lshl_add_u64 v[148:149], s[2:3], 0, v[138:139]
	v_lshl_add_u64 v[150:151], s[8:9], 0, v[138:139]
	v_lshl_add_u64 v[186:187], v[0:1], 0, s[6:7]
	s_mov_b64 s[16:17], 0
	v_mov_b32_e32 v147, v132
	s_mov_b64 s[8:9], 0x1000
	v_lshl_add_u64 v[218:219], v[148:149], 0, s[8:9]
	global_load_dwordx4 v[154:157], v[148:149], off
	global_load_dwordx4 v[158:161], v[148:149], off offset:1024
	global_load_dwordx4 v[162:165], v[148:149], off offset:2048
	global_load_dwordx4 v[166:169], v[148:149], off offset:3072
	global_load_dwordx4 v[170:173], v[218:219], off
	global_load_dwordx4 v[174:177], v[218:219], off offset:1024
	global_load_dwordx4 v[178:181], v[218:219], off offset:2048
	global_load_dwordx4 v[182:185], v[218:219], off offset:3072
	v_lshl_add_u64 v[218:219], v[152:153], 0, s[8:9]
	global_load_dwordx4 v[186:189], v[152:153], off
	global_load_dwordx4 v[190:193], v[152:153], off offset:1024
	global_load_dwordx4 v[194:197], v[152:153], off offset:2048
	global_load_dwordx4 v[198:201], v[152:153], off offset:3072
	global_load_dwordx4 v[202:205], v[218:219], off
	global_load_dwordx4 v[206:209], v[218:219], off offset:1024
	global_load_dwordx4 v[210:213], v[218:219], off offset:2048
	global_load_dwordx4 v[214:217], v[218:219], off offset:3072
	v_lshl_add_u64 v[218:219], v[150:151], 0, s[8:9]
	global_load_dwordx4 v[0:3], v[150:151], off
	global_load_dwordx4 v[4:7], v[150:151], off offset:1024
	global_load_dwordx4 v[8:11], v[150:151], off offset:2048
	global_load_dwordx4 v[12:15], v[150:151], off offset:3072
	global_load_dwordx4 v[16:19], v[218:219], off
	global_load_dwordx4 v[20:23], v[218:219], off offset:1024
	global_load_dwordx4 v[24:27], v[218:219], off offset:2048
	global_load_dwordx4 v[28:31], v[218:219], off offset:3072
	s_waitcnt vmcnt(0)
; __device__ __forceinline__ void norm_rows(const float* src, int nrows, const float* gam, const float* sc, const float* sh, bf16_t* dst, int tid) {
;     ...
;   for (int r0 = gw; r0 < nrows; r0 += 4 * nw) {
;     f32x4 v[4][8]; float ss[4]; int rr[4]; bool ok[4];
; #pragma unroll
;     for (int q = 0; q < 4; ++q) { const int r = r0 + q * nw; ok[q] = r < nrows; rr[q] = ok[q] ? r : r0; }
; #pragma unroll
;     for (int q = 0; q < 4; ++q) { const f32x4* xr = (const f32x4*)(src + (size_t)rr[q] * DM) + lane;
; #pragma unroll
;       for (int j = 0; j < 8; ++j) v[q][j] = xr[64 * j]; }
; #pragma unroll
;     for (int q = 0; q < 4; ++q) { float s = 0.f;
; #pragma unroll
;       for (int j = 0; j < 8; ++j) s += v[q][j][0] * v[q][j][0] + v[q][j][1] * v[q][j][1] + v[q][j][2] * v[q][j][2] + v[q][j][3] * v[q][j][3];
;       ss[q] = rsqrtf(wave_sum(s) * (1.0f / DM) + 1e-6f); }
;     ...
;       const f32x4 mul = *(const f32x4*)(gam + c) * (1.0f + *(const f32x4*)(sc + c)); const f32x4 add = *(const f32x4*)(sh + c);
	v_pk_add_f32 v[0:1], v[0:1], 1.0 op_sel_hi:[1,0]
	v_pk_mul_f32 v[154:155], v[154:155], v[0:1]
	v_pk_add_f32 v[2:3], v[2:3], 1.0 op_sel_hi:[1,0]
	v_pk_mul_f32 v[156:157], v[156:157], v[2:3]
	v_pk_add_f32 v[4:5], v[4:5], 1.0 op_sel_hi:[1,0]
	v_pk_mul_f32 v[158:159], v[158:159], v[4:5]
	v_pk_add_f32 v[6:7], v[6:7], 1.0 op_sel_hi:[1,0]
	v_pk_mul_f32 v[160:161], v[160:161], v[6:7]
	v_pk_add_f32 v[8:9], v[8:9], 1.0 op_sel_hi:[1,0]
	v_pk_mul_f32 v[162:163], v[162:163], v[8:9]
	v_pk_add_f32 v[10:11], v[10:11], 1.0 op_sel_hi:[1,0]
	v_pk_mul_f32 v[164:165], v[164:165], v[10:11]
	v_pk_add_f32 v[12:13], v[12:13], 1.0 op_sel_hi:[1,0]
	v_pk_mul_f32 v[166:167], v[166:167], v[12:13]
	v_pk_add_f32 v[14:15], v[14:15], 1.0 op_sel_hi:[1,0]
	v_pk_mul_f32 v[168:169], v[168:169], v[14:15]
	v_pk_add_f32 v[16:17], v[16:17], 1.0 op_sel_hi:[1,0]
	v_pk_mul_f32 v[170:171], v[170:171], v[16:17]
	v_pk_add_f32 v[18:19], v[18:19], 1.0 op_sel_hi:[1,0]
	v_pk_mul_f32 v[172:173], v[172:173], v[18:19]
	v_pk_add_f32 v[20:21], v[20:21], 1.0 op_sel_hi:[1,0]
	v_pk_mul_f32 v[174:175], v[174:175], v[20:21]
	v_pk_add_f32 v[22:23], v[22:23], 1.0 op_sel_hi:[1,0]
	v_pk_mul_f32 v[176:177], v[176:177], v[22:23]
	v_pk_add_f32 v[24:25], v[24:25], 1.0 op_sel_hi:[1,0]
	v_pk_mul_f32 v[178:179], v[178:179], v[24:25]
	v_pk_add_f32 v[26:27], v[26:27], 1.0 op_sel_hi:[1,0]
	v_pk_mul_f32 v[180:181], v[180:181], v[26:27]
	v_pk_add_f32 v[28:29], v[28:29], 1.0 op_sel_hi:[1,0]
	v_pk_mul_f32 v[182:183], v[182:183], v[28:29]
	v_pk_add_f32 v[30:31], v[30:31], 1.0 op_sel_hi:[1,0]
	v_pk_mul_f32 v[184:185], v[184:185], v[30:31]
	v_mbcnt_lo_u32_b32 v153, -1, 0
	v_mbcnt_hi_u32_b32 v153, -1, v153
	v_lshlrev_b32_e32 v153, 2, v153
	v_xor_b32_e32 v140, 4, v153
	v_xor_b32_e32 v141, 8, v153
	v_xor_b32_e32 v142, 16, v153
	v_xor_b32_e32 v150, 32, v153
	v_xor_b32_e32 v151, 64, v153
	v_xor_b32_e32 v152, 0x80, v153
	s_nop 0
	v_readfirstlane_b32 s6, v147
	s_mov_b32 s7, s6
	s_mov_b32 s11, s6
	s_cmp_lt_i32 s7, 0x4000
	s_cselect_b32 s10, s7, s11
	s_lshl_b32 s8, s10, 13
	s_add_u32 s8, s8, 0x1000
	s_mov_b32 s9, 0
	v_lshl_add_u64 v[244:245], v[134:135], 0, s[8:9]
	global_load_dwordx4 v[0:3], v[244:245], off offset:-4096
	global_load_dwordx4 v[4:7], v[244:245], off offset:-3072
	global_load_dwordx4 v[8:11], v[244:245], off offset:-2048
	global_load_dwordx4 v[12:15], v[244:245], off offset:-1024
	global_load_dwordx4 v[16:19], v[244:245], off
	global_load_dwordx4 v[20:23], v[244:245], off offset:1024
	global_load_dwordx4 v[24:27], v[244:245], off offset:2048
	global_load_dwordx4 v[28:31], v[244:245], off offset:3072
	s_add_i32 s7, s7, s82
	s_cmp_lt_i32 s7, 0x4000
	s_cselect_b32 s10, s7, s11
	s_lshl_b32 s8, s10, 13
	s_add_u32 s8, s8, 0x1000
	s_mov_b32 s9, 0
	v_lshl_add_u64 v[246:247], v[134:135], 0, s[8:9]
	global_load_dwordx4 v[32:35], v[246:247], off offset:-4096
	global_load_dwordx4 v[36:39], v[246:247], off offset:-3072
	global_load_dwordx4 v[40:43], v[246:247], off offset:-2048
	global_load_dwordx4 v[44:47], v[246:247], off offset:-1024
	global_load_dwordx4 v[48:51], v[246:247], off
	global_load_dwordx4 v[52:55], v[246:247], off offset:1024
	global_load_dwordx4 v[56:59], v[246:247], off offset:2048
	global_load_dwordx4 v[60:63], v[246:247], off offset:3072
	s_add_i32 s7, s7, s82
	s_cmp_lt_i32 s7, 0x4000
	s_cselect_b32 s10, s7, s11
	s_lshl_b32 s8, s10, 13
	s_add_u32 s8, s8, 0x1000
	s_mov_b32 s9, 0
	v_lshl_add_u64 v[248:249], v[134:135], 0, s[8:9]
	global_load_dwordx4 v[64:67], v[248:249], off offset:-4096
	global_load_dwordx4 v[68:71], v[248:249], off offset:-3072
	global_load_dwordx4 v[72:75], v[248:249], off offset:-2048
	global_load_dwordx4 v[76:79], v[248:249], off offset:-1024
	global_load_dwordx4 v[80:83], v[248:249], off
	global_load_dwordx4 v[84:87], v[248:249], off offset:1024
	global_load_dwordx4 v[88:91], v[248:249], off offset:2048
	global_load_dwordx4 v[92:95], v[248:249], off offset:3072
	s_add_i32 s7, s7, s82
	s_cmp_lt_i32 s7, 0x4000
	s_cselect_b32 s10, s7, s11
	s_lshl_b32 s8, s10, 13
	s_add_u32 s8, s8, 0x1000
	s_mov_b32 s9, 0
	v_lshl_add_u64 v[250:251], v[134:135], 0, s[8:9]
	global_load_dwordx4 v[96:99], v[250:251], off offset:-4096
	global_load_dwordx4 v[100:103], v[250:251], off offset:-3072
	global_load_dwordx4 v[104:107], v[250:251], off offset:-2048
	global_load_dwordx4 v[108:111], v[250:251], off offset:-1024
	global_load_dwordx4 v[112:115], v[250:251], off
	global_load_dwordx4 v[116:119], v[250:251], off offset:1024
	global_load_dwordx4 v[120:123], v[250:251], off offset:2048
	global_load_dwordx4 v[124:127], v[250:251], off offset:3072
	s_add_i32 s7, s7, s82
	s_waitcnt vmcnt(24)
	v_pk_mul_f32 v[218:219], v[0:1], v[0:1]
	v_pk_fma_f32 v[218:219], v[2:3], v[2:3], v[218:219]
	v_pk_mul_f32 v[220:221], v[4:5], v[4:5]
	v_pk_fma_f32 v[220:221], v[6:7], v[6:7], v[220:221]
	v_pk_mul_f32 v[222:223], v[8:9], v[8:9]
	v_pk_fma_f32 v[222:223], v[10:11], v[10:11], v[222:223]
	v_pk_mul_f32 v[224:225], v[12:13], v[12:13]
	v_pk_fma_f32 v[224:225], v[14:15], v[14:15], v[224:225]
	v_pk_fma_f32 v[218:219], v[16:17], v[16:17], v[218:219]
	v_pk_fma_f32 v[218:219], v[18:19], v[18:19], v[218:219]
	v_pk_fma_f32 v[220:221], v[20:21], v[20:21], v[220:221]
	v_pk_fma_f32 v[220:221], v[22:23], v[22:23], v[220:221]
	v_pk_fma_f32 v[222:223], v[24:25], v[24:25], v[222:223]
	v_pk_fma_f32 v[222:223], v[26:27], v[26:27], v[222:223]
	v_pk_fma_f32 v[224:225], v[28:29], v[28:29], v[224:225]
	v_pk_fma_f32 v[224:225], v[30:31], v[30:31], v[224:225]
	v_pk_add_f32 v[218:219], v[218:219], v[220:221]
	v_pk_add_f32 v[222:223], v[222:223], v[224:225]
	v_pk_add_f32 v[218:219], v[218:219], v[222:223]
	v_add_f32_e32 v128, v218, v219
	ds_bpermute_b32 v129, v140, v128
	s_waitcnt lgkmcnt(0)
; __device__ __forceinline__ unsigned cvt_pk_bf16(float lo, float hi) { unsigned r; asm volatile("v_cvt_pk_bf16_f32 %0, %1, %2" : "=v"(r) : "v"(lo), "v"(hi)); return r; }
; __device__ __forceinline__ void norm_rows(const float* src, int nrows, const float* gam, const float* sc, const float* sh, bf16_t* dst, int tid) {
;     ...
;       ss[q] = rsqrtf(wave_sum(s) * (1.0f / DM) + 1e-6f); }
; #pragma unroll
;     for (int j = 0; j < 8; ++j) {
;       const int c = 4 * (lane + 64 * j);
;       const f32x4 mul = *(const f32x4*)(gam + c) * (1.0f + *(const f32x4*)(sc + c)); const f32x4 add = *(const f32x4*)(sh + c);
; #pragma unroll
;       for (int q = 0; q < 4; ++q) if (ok[q]) {
;         const f32x4 h = v[q][j] * ss[q] * mul + add; u32x2 w; w.x = cvt_pk_bf16(h[0], h[1]); w.y = cvt_pk_bf16(h[2], h[3]);
;         ((u32x2*)(dst + (size_t)rr[q] * DM) + lane)[64 * j] = w;
;       }
	v_add_f32_e32 v128, v128, v129
	ds_bpermute_b32 v129, v141, v128
	s_waitcnt lgkmcnt(0)
	v_add_f32_e32 v128, v128, v129
	ds_bpermute_b32 v129, v142, v128
	s_waitcnt lgkmcnt(0)
	v_add_f32_e32 v128, v128, v129
	ds_bpermute_b32 v129, v150, v128
	s_waitcnt lgkmcnt(0)
	v_add_f32_e32 v128, v128, v129
	ds_bpermute_b32 v129, v151, v128
	s_waitcnt lgkmcnt(0)
	v_add_f32_e32 v128, v128, v129
	ds_bpermute_b32 v129, v152, v128
	s_waitcnt lgkmcnt(0)
	v_add_f32_e32 v128, v128, v129
	v_fmamk_f32 v128, v128, 0x3a000000, v228
	v_mul_f32_e32 v129, 0x4b800000, v128
	v_cmp_gt_f32_e32 vcc, s67, v128
	s_nop 1
	v_cndmask_b32_e32 v128, v128, v129, vcc
	v_rsq_f32_e32 v128, v128
	s_nop 0
	v_mul_f32_e32 v129, 0x45800000, v128
	v_cndmask_b32_e32 v128, v128, v129, vcc
	s_lshl_b32 s8, s6, 12
	s_add_u32 s8, s8, 0x800
	s_mov_b32 s9, 0
	v_lshl_add_u64 v[230:231], v[136:137], 0, s[8:9]
	v_pk_mul_f32 v[0:1], v[0:1], v[128:129] op_sel_hi:[1,0]
	v_pk_fma_f32 v[0:1], v[0:1], v[154:155], v[186:187]
	v_pk_mul_f32 v[2:3], v[2:3], v[128:129] op_sel_hi:[1,0]
	v_pk_fma_f32 v[2:3], v[2:3], v[156:157], v[188:189]
	v_cvt_pk_bf16_f32 v0, v0, v1
	v_cvt_pk_bf16_f32 v1, v2, v3
	global_store_dwordx2 v[230:231], v[0:1], off offset:-2048
	v_pk_mul_f32 v[4:5], v[4:5], v[128:129] op_sel_hi:[1,0]
	v_pk_fma_f32 v[4:5], v[4:5], v[158:159], v[190:191]
	v_pk_mul_f32 v[6:7], v[6:7], v[128:129] op_sel_hi:[1,0]
	v_pk_fma_f32 v[6:7], v[6:7], v[160:161], v[192:193]
	v_cvt_pk_bf16_f32 v4, v4, v5
	v_cvt_pk_bf16_f32 v5, v6, v7
	global_store_dwordx2 v[230:231], v[4:5], off offset:-1536
	v_pk_mul_f32 v[8:9], v[8:9], v[128:129] op_sel_hi:[1,0]
	v_pk_fma_f32 v[8:9], v[8:9], v[162:163], v[194:195]
	v_pk_mul_f32 v[10:11], v[10:11], v[128:129] op_sel_hi:[1,0]
	v_pk_fma_f32 v[10:11], v[10:11], v[164:165], v[196:197]
	v_cvt_pk_bf16_f32 v8, v8, v9
	v_cvt_pk_bf16_f32 v9, v10, v11
	global_store_dwordx2 v[230:231], v[8:9], off offset:-1024
	v_pk_mul_f32 v[12:13], v[12:13], v[128:129] op_sel_hi:[1,0]
	v_pk_fma_f32 v[12:13], v[12:13], v[166:167], v[198:199]
	v_pk_mul_f32 v[14:15], v[14:15], v[128:129] op_sel_hi:[1,0]
	v_pk_fma_f32 v[14:15], v[14:15], v[168:169], v[200:201]
	v_cvt_pk_bf16_f32 v12, v12, v13
	v_cvt_pk_bf16_f32 v13, v14, v15
	global_store_dwordx2 v[230:231], v[12:13], off offset:-512
	v_pk_mul_f32 v[16:17], v[16:17], v[128:129] op_sel_hi:[1,0]
	v_pk_fma_f32 v[16:17], v[16:17], v[170:171], v[202:203]
	v_pk_mul_f32 v[18:19], v[18:19], v[128:129] op_sel_hi:[1,0]
	v_pk_fma_f32 v[18:19], v[18:19], v[172:173], v[204:205]
	v_cvt_pk_bf16_f32 v16, v16, v17
	v_cvt_pk_bf16_f32 v17, v18, v19
	global_store_dwordx2 v[230:231], v[16:17], off
	v_pk_mul_f32 v[20:21], v[20:21], v[128:129] op_sel_hi:[1,0]
	v_pk_fma_f32 v[20:21], v[20:21], v[174:175], v[206:207]
	v_pk_mul_f32 v[22:23], v[22:23], v[128:129] op_sel_hi:[1,0]
	v_pk_fma_f32 v[22:23], v[22:23], v[176:177], v[208:209]
	v_cvt_pk_bf16_f32 v20, v20, v21
	v_cvt_pk_bf16_f32 v21, v22, v23
	global_store_dwordx2 v[230:231], v[20:21], off offset:512
	v_pk_mul_f32 v[24:25], v[24:25], v[128:129] op_sel_hi:[1,0]
	v_pk_fma_f32 v[24:25], v[24:25], v[178:179], v[210:211]
	v_pk_mul_f32 v[26:27], v[26:27], v[128:129] op_sel_hi:[1,0]
	v_pk_fma_f32 v[26:27], v[26:27], v[180:181], v[212:213]
	v_cvt_pk_bf16_f32 v24, v24, v25
	v_cvt_pk_bf16_f32 v25, v26, v27
	global_store_dwordx2 v[230:231], v[24:25], off offset:1024
	v_pk_mul_f32 v[28:29], v[28:29], v[128:129] op_sel_hi:[1,0]
	v_pk_fma_f32 v[28:29], v[28:29], v[182:183], v[214:215]
	v_pk_mul_f32 v[30:31], v[30:31], v[128:129] op_sel_hi:[1,0]
	v_pk_fma_f32 v[30:31], v[30:31], v[184:185], v[216:217]
	v_cvt_pk_bf16_f32 v28, v28, v29
	v_cvt_pk_bf16_f32 v29, v30, v31
	global_store_dwordx2 v[230:231], v[28:29], off offset:1536
	s_add_i32 s6, s6, s82
	s_cmp_lt_i32 s6, 0x4000
	s_cbranch_scc0 .Lnr_done
	s_cmp_lt_i32 s7, 0x4000
	s_cselect_b32 s10, s7, s11
	s_lshl_b32 s8, s10, 13
	s_add_u32 s8, s8, 0x1000
	s_mov_b32 s9, 0
	v_lshl_add_u64 v[244:245], v[134:135], 0, s[8:9]
	global_load_dwordx4 v[0:3], v[244:245], off offset:-4096
	global_load_dwordx4 v[4:7], v[244:245], off offset:-3072
	global_load_dwordx4 v[8:11], v[244:245], off offset:-2048
	global_load_dwordx4 v[12:15], v[244:245], off offset:-1024
	global_load_dwordx4 v[16:19], v[244:245], off
	global_load_dwordx4 v[20:23], v[244:245], off offset:1024
	global_load_dwordx4 v[24:27], v[244:245], off offset:2048
	global_load_dwordx4 v[28:31], v[244:245], off offset:3072
	s_add_i32 s7, s7, s82
	s_waitcnt vmcnt(32)
	v_pk_mul_f32 v[218:219], v[32:33], v[32:33]
	v_pk_fma_f32 v[218:219], v[34:35], v[34:35], v[218:219]
	v_pk_mul_f32 v[220:221], v[36:37], v[36:37]
	v_pk_fma_f32 v[220:221], v[38:39], v[38:39], v[220:221]
	v_pk_mul_f32 v[222:223], v[40:41], v[40:41]
	v_pk_fma_f32 v[222:223], v[42:43], v[42:43], v[222:223]
	v_pk_mul_f32 v[224:225], v[44:45], v[44:45]
	v_pk_fma_f32 v[224:225], v[46:47], v[46:47], v[224:225]
	v_pk_fma_f32 v[218:219], v[48:49], v[48:49], v[218:219]
	v_pk_fma_f32 v[218:219], v[50:51], v[50:51], v[218:219]
	v_pk_fma_f32 v[220:221], v[52:53], v[52:53], v[220:221]
	v_pk_fma_f32 v[220:221], v[54:55], v[54:55], v[220:221]
	v_pk_fma_f32 v[222:223], v[56:57], v[56:57], v[222:223]
	v_pk_fma_f32 v[222:223], v[58:59], v[58:59], v[222:223]
	v_pk_fma_f32 v[224:225], v[60:61], v[60:61], v[224:225]
	v_pk_fma_f32 v[224:225], v[62:63], v[62:63], v[224:225]
	v_pk_add_f32 v[218:219], v[218:219], v[220:221]
	v_pk_add_f32 v[222:223], v[222:223], v[224:225]
	v_pk_add_f32 v[218:219], v[218:219], v[222:223]
	v_add_f32_e32 v128, v218, v219
	ds_bpermute_b32 v129, v140, v128
	s_waitcnt lgkmcnt(0)
	v_add_f32_e32 v128, v128, v129
	ds_bpermute_b32 v129, v141, v128
	s_waitcnt lgkmcnt(0)
; __device__ __forceinline__ unsigned cvt_pk_bf16(float lo, float hi) { unsigned r; asm volatile("v_cvt_pk_bf16_f32 %0, %1, %2" : "=v"(r) : "v"(lo), "v"(hi)); return r; }
; __device__ __forceinline__ void norm_rows(const float* src, int nrows, const float* gam, const float* sc, const float* sh, bf16_t* dst, int tid) {
;     ...
;       ss[q] = rsqrtf(wave_sum(s) * (1.0f / DM) + 1e-6f); }
; #pragma unroll
;     for (int j = 0; j < 8; ++j) {
;       const int c = 4 * (lane + 64 * j);
;       const f32x4 mul = *(const f32x4*)(gam + c) * (1.0f + *(const f32x4*)(sc + c)); const f32x4 add = *(const f32x4*)(sh + c);
; #pragma unroll
;       for (int q = 0; q < 4; ++q) if (ok[q]) {
;         const f32x4 h = v[q][j] * ss[q] * mul + add; u32x2 w; w.x = cvt_pk_bf16(h[0], h[1]); w.y = cvt_pk_bf16(h[2], h[3]);
;         ((u32x2*)(dst + (size_t)rr[q] * DM) + lane)[64 * j] = w;
;       }
	v_add_f32_e32 v128, v128, v129
	ds_bpermute_b32 v129, v142, v128
	s_waitcnt lgkmcnt(0)
	v_add_f32_e32 v128, v128, v129
	ds_bpermute_b32 v129, v150, v128
	s_waitcnt lgkmcnt(0)
	v_add_f32_e32 v128, v128, v129
	ds_bpermute_b32 v129, v151, v128
	s_waitcnt lgkmcnt(0)
	v_add_f32_e32 v128, v128, v129
	ds_bpermute_b32 v129, v152, v128
	s_waitcnt lgkmcnt(0)
	v_add_f32_e32 v128, v128, v129
	v_fmamk_f32 v128, v128, 0x3a000000, v228
	v_mul_f32_e32 v129, 0x4b800000, v128
	v_cmp_gt_f32_e32 vcc, s67, v128
	s_nop 1
	v_cndmask_b32_e32 v128, v128, v129, vcc
	v_rsq_f32_e32 v128, v128
	s_nop 0
	v_mul_f32_e32 v129, 0x45800000, v128
	v_cndmask_b32_e32 v128, v128, v129, vcc
	s_lshl_b32 s8, s6, 12
	s_add_u32 s8, s8, 0x800
	s_mov_b32 s9, 0
	v_lshl_add_u64 v[230:231], v[136:137], 0, s[8:9]
	v_pk_mul_f32 v[32:33], v[32:33], v[128:129] op_sel_hi:[1,0]
	v_pk_fma_f32 v[32:33], v[32:33], v[154:155], v[186:187]
	v_pk_mul_f32 v[34:35], v[34:35], v[128:129] op_sel_hi:[1,0]
	v_pk_fma_f32 v[34:35], v[34:35], v[156:157], v[188:189]
	v_cvt_pk_bf16_f32 v32, v32, v33
	v_cvt_pk_bf16_f32 v33, v34, v35
	global_store_dwordx2 v[230:231], v[32:33], off offset:-2048
	v_pk_mul_f32 v[36:37], v[36:37], v[128:129] op_sel_hi:[1,0]
	v_pk_fma_f32 v[36:37], v[36:37], v[158:159], v[190:191]
	v_pk_mul_f32 v[38:39], v[38:39], v[128:129] op_sel_hi:[1,0]
	v_pk_fma_f32 v[38:39], v[38:39], v[160:161], v[192:193]
	v_cvt_pk_bf16_f32 v36, v36, v37
	v_cvt_pk_bf16_f32 v37, v38, v39
	global_store_dwordx2 v[230:231], v[36:37], off offset:-1536
	v_pk_mul_f32 v[40:41], v[40:41], v[128:129] op_sel_hi:[1,0]
	v_pk_fma_f32 v[40:41], v[40:41], v[162:163], v[194:195]
	v_pk_mul_f32 v[42:43], v[42:43], v[128:129] op_sel_hi:[1,0]
	v_pk_fma_f32 v[42:43], v[42:43], v[164:165], v[196:197]
	v_cvt_pk_bf16_f32 v40, v40, v41
	v_cvt_pk_bf16_f32 v41, v42, v43
	global_store_dwordx2 v[230:231], v[40:41], off offset:-1024
	v_pk_mul_f32 v[44:45], v[44:45], v[128:129] op_sel_hi:[1,0]
	v_pk_fma_f32 v[44:45], v[44:45], v[166:167], v[198:199]
	v_pk_mul_f32 v[46:47], v[46:47], v[128:129] op_sel_hi:[1,0]
	v_pk_fma_f32 v[46:47], v[46:47], v[168:169], v[200:201]
	v_cvt_pk_bf16_f32 v44, v44, v45
	v_cvt_pk_bf16_f32 v45, v46, v47
	global_store_dwordx2 v[230:231], v[44:45], off offset:-512
	v_pk_mul_f32 v[48:49], v[48:49], v[128:129] op_sel_hi:[1,0]
	v_pk_fma_f32 v[48:49], v[48:49], v[170:171], v[202:203]
	v_pk_mul_f32 v[50:51], v[50:51], v[128:129] op_sel_hi:[1,0]
	v_pk_fma_f32 v[50:51], v[50:51], v[172:173], v[204:205]
	v_cvt_pk_bf16_f32 v48, v48, v49
	v_cvt_pk_bf16_f32 v49, v50, v51
	global_store_dwordx2 v[230:231], v[48:49], off
	v_pk_mul_f32 v[52:53], v[52:53], v[128:129] op_sel_hi:[1,0]
	v_pk_fma_f32 v[52:53], v[52:53], v[174:175], v[206:207]
	v_pk_mul_f32 v[54:55], v[54:55], v[128:129] op_sel_hi:[1,0]
	v_pk_fma_f32 v[54:55], v[54:55], v[176:177], v[208:209]
	v_cvt_pk_bf16_f32 v52, v52, v53
	v_cvt_pk_bf16_f32 v53, v54, v55
	global_store_dwordx2 v[230:231], v[52:53], off offset:512
	v_pk_mul_f32 v[56:57], v[56:57], v[128:129] op_sel_hi:[1,0]
	v_pk_fma_f32 v[56:57], v[56:57], v[178:179], v[210:211]
	v_pk_mul_f32 v[58:59], v[58:59], v[128:129] op_sel_hi:[1,0]
	v_pk_fma_f32 v[58:59], v[58:59], v[180:181], v[212:213]
	v_cvt_pk_bf16_f32 v56, v56, v57
	v_cvt_pk_bf16_f32 v57, v58, v59
	global_store_dwordx2 v[230:231], v[56:57], off offset:1024
	v_pk_mul_f32 v[60:61], v[60:61], v[128:129] op_sel_hi:[1,0]
	v_pk_fma_f32 v[60:61], v[60:61], v[182:183], v[214:215]
	v_pk_mul_f32 v[62:63], v[62:63], v[128:129] op_sel_hi:[1,0]
	v_pk_fma_f32 v[62:63], v[62:63], v[184:185], v[216:217]
	v_cvt_pk_bf16_f32 v60, v60, v61
	v_cvt_pk_bf16_f32 v61, v62, v63
	global_store_dwordx2 v[230:231], v[60:61], off offset:1536
	s_add_i32 s6, s6, s82
	s_cmp_lt_i32 s6, 0x4000
	s_cbranch_scc0 .Lnr_done
	s_cmp_lt_i32 s7, 0x4000
	s_cselect_b32 s10, s7, s11
	s_lshl_b32 s8, s10, 13
	s_add_u32 s8, s8, 0x1000
	s_mov_b32 s9, 0
	v_lshl_add_u64 v[246:247], v[134:135], 0, s[8:9]
	global_load_dwordx4 v[32:35], v[246:247], off offset:-4096
	global_load_dwordx4 v[36:39], v[246:247], off offset:-3072
	global_load_dwordx4 v[40:43], v[246:247], off offset:-2048
	global_load_dwordx4 v[44:47], v[246:247], off offset:-1024
	global_load_dwordx4 v[48:51], v[246:247], off
	global_load_dwordx4 v[52:55], v[246:247], off offset:1024
	global_load_dwordx4 v[56:59], v[246:247], off offset:2048
	global_load_dwordx4 v[60:63], v[246:247], off offset:3072
	s_add_i32 s7, s7, s82
	s_waitcnt vmcnt(40)
	v_pk_mul_f32 v[218:219], v[64:65], v[64:65]
	v_pk_fma_f32 v[218:219], v[66:67], v[66:67], v[218:219]
	v_pk_mul_f32 v[220:221], v[68:69], v[68:69]
	v_pk_fma_f32 v[220:221], v[70:71], v[70:71], v[220:221]
	v_pk_mul_f32 v[222:223], v[72:73], v[72:73]
	v_pk_fma_f32 v[222:223], v[74:75], v[74:75], v[222:223]
	v_pk_mul_f32 v[224:225], v[76:77], v[76:77]
	v_pk_fma_f32 v[224:225], v[78:79], v[78:79], v[224:225]
	v_pk_fma_f32 v[218:219], v[80:81], v[80:81], v[218:219]
	v_pk_fma_f32 v[218:219], v[82:83], v[82:83], v[218:219]
	v_pk_fma_f32 v[220:221], v[84:85], v[84:85], v[220:221]
	v_pk_fma_f32 v[220:221], v[86:87], v[86:87], v[220:221]
	v_pk_fma_f32 v[222:223], v[88:89], v[88:89], v[222:223]
	v_pk_fma_f32 v[222:223], v[90:91], v[90:91], v[222:223]
	v_pk_fma_f32 v[224:225], v[92:93], v[92:93], v[224:225]
	v_pk_fma_f32 v[224:225], v[94:95], v[94:95], v[224:225]
	v_pk_add_f32 v[218:219], v[218:219], v[220:221]
	v_pk_add_f32 v[222:223], v[222:223], v[224:225]
	v_pk_add_f32 v[218:219], v[218:219], v[222:223]
	v_add_f32_e32 v128, v218, v219
	ds_bpermute_b32 v129, v140, v128
	s_waitcnt lgkmcnt(0)
	v_add_f32_e32 v128, v128, v129
	ds_bpermute_b32 v129, v141, v128
	s_waitcnt lgkmcnt(0)
; __device__ __forceinline__ unsigned cvt_pk_bf16(float lo, float hi) { unsigned r; asm volatile("v_cvt_pk_bf16_f32 %0, %1, %2" : "=v"(r) : "v"(lo), "v"(hi)); return r; }
; __device__ __forceinline__ void norm_rows(const float* src, int nrows, const float* gam, const float* sc, const float* sh, bf16_t* dst, int tid) {
;     ...
;       ss[q] = rsqrtf(wave_sum(s) * (1.0f / DM) + 1e-6f); }
; #pragma unroll
;     for (int j = 0; j < 8; ++j) {
;       const int c = 4 * (lane + 64 * j);
;       const f32x4 mul = *(const f32x4*)(gam + c) * (1.0f + *(const f32x4*)(sc + c)); const f32x4 add = *(const f32x4*)(sh + c);
; #pragma unroll
;       for (int q = 0; q < 4; ++q) if (ok[q]) {
;         const f32x4 h = v[q][j] * ss[q] * mul + add; u32x2 w; w.x = cvt_pk_bf16(h[0], h[1]); w.y = cvt_pk_bf16(h[2], h[3]);
;         ((u32x2*)(dst + (size_t)rr[q] * DM) + lane)[64 * j] = w;
;       }
	v_add_f32_e32 v128, v128, v129
	ds_bpermute_b32 v129, v142, v128
	s_waitcnt lgkmcnt(0)
	v_add_f32_e32 v128, v128, v129
	ds_bpermute_b32 v129, v150, v128
	s_waitcnt lgkmcnt(0)
	v_add_f32_e32 v128, v128, v129
	ds_bpermute_b32 v129, v151, v128
	s_waitcnt lgkmcnt(0)
	v_add_f32_e32 v128, v128, v129
	ds_bpermute_b32 v129, v152, v128
	s_waitcnt lgkmcnt(0)
	v_add_f32_e32 v128, v128, v129
	v_fmamk_f32 v128, v128, 0x3a000000, v228
	v_mul_f32_e32 v129, 0x4b800000, v128
	v_cmp_gt_f32_e32 vcc, s67, v128
	s_nop 1
	v_cndmask_b32_e32 v128, v128, v129, vcc
	v_rsq_f32_e32 v128, v128
	s_nop 0
	v_mul_f32_e32 v129, 0x45800000, v128
	v_cndmask_b32_e32 v128, v128, v129, vcc
	s_lshl_b32 s8, s6, 12
	s_add_u32 s8, s8, 0x800
	s_mov_b32 s9, 0
	v_lshl_add_u64 v[230:231], v[136:137], 0, s[8:9]
	v_pk_mul_f32 v[64:65], v[64:65], v[128:129] op_sel_hi:[1,0]
	v_pk_fma_f32 v[64:65], v[64:65], v[154:155], v[186:187]
	v_pk_mul_f32 v[66:67], v[66:67], v[128:129] op_sel_hi:[1,0]
	v_pk_fma_f32 v[66:67], v[66:67], v[156:157], v[188:189]
	v_cvt_pk_bf16_f32 v64, v64, v65
	v_cvt_pk_bf16_f32 v65, v66, v67
	global_store_dwordx2 v[230:231], v[64:65], off offset:-2048
	v_pk_mul_f32 v[68:69], v[68:69], v[128:129] op_sel_hi:[1,0]
	v_pk_fma_f32 v[68:69], v[68:69], v[158:159], v[190:191]
	v_pk_mul_f32 v[70:71], v[70:71], v[128:129] op_sel_hi:[1,0]
	v_pk_fma_f32 v[70:71], v[70:71], v[160:161], v[192:193]
	v_cvt_pk_bf16_f32 v68, v68, v69
	v_cvt_pk_bf16_f32 v69, v70, v71
	global_store_dwordx2 v[230:231], v[68:69], off offset:-1536
	v_pk_mul_f32 v[72:73], v[72:73], v[128:129] op_sel_hi:[1,0]
	v_pk_fma_f32 v[72:73], v[72:73], v[162:163], v[194:195]
	v_pk_mul_f32 v[74:75], v[74:75], v[128:129] op_sel_hi:[1,0]
	v_pk_fma_f32 v[74:75], v[74:75], v[164:165], v[196:197]
	v_cvt_pk_bf16_f32 v72, v72, v73
	v_cvt_pk_bf16_f32 v73, v74, v75
	global_store_dwordx2 v[230:231], v[72:73], off offset:-1024
	v_pk_mul_f32 v[76:77], v[76:77], v[128:129] op_sel_hi:[1,0]
	v_pk_fma_f32 v[76:77], v[76:77], v[166:167], v[198:199]
	v_pk_mul_f32 v[78:79], v[78:79], v[128:129] op_sel_hi:[1,0]
	v_pk_fma_f32 v[78:79], v[78:79], v[168:169], v[200:201]
	v_cvt_pk_bf16_f32 v76, v76, v77
	v_cvt_pk_bf16_f32 v77, v78, v79
	global_store_dwordx2 v[230:231], v[76:77], off offset:-512
	v_pk_mul_f32 v[80:81], v[80:81], v[128:129] op_sel_hi:[1,0]
	v_pk_fma_f32 v[80:81], v[80:81], v[170:171], v[202:203]
	v_pk_mul_f32 v[82:83], v[82:83], v[128:129] op_sel_hi:[1,0]
	v_pk_fma_f32 v[82:83], v[82:83], v[172:173], v[204:205]
	v_cvt_pk_bf16_f32 v80, v80, v81
	v_cvt_pk_bf16_f32 v81, v82, v83
	global_store_dwordx2 v[230:231], v[80:81], off
	v_pk_mul_f32 v[84:85], v[84:85], v[128:129] op_sel_hi:[1,0]
	v_pk_fma_f32 v[84:85], v[84:85], v[174:175], v[206:207]
	v_pk_mul_f32 v[86:87], v[86:87], v[128:129] op_sel_hi:[1,0]
	v_pk_fma_f32 v[86:87], v[86:87], v[176:177], v[208:209]
	v_cvt_pk_bf16_f32 v84, v84, v85
	v_cvt_pk_bf16_f32 v85, v86, v87
	global_store_dwordx2 v[230:231], v[84:85], off offset:512
	v_pk_mul_f32 v[88:89], v[88:89], v[128:129] op_sel_hi:[1,0]
	v_pk_fma_f32 v[88:89], v[88:89], v[178:179], v[210:211]
	v_pk_mul_f32 v[90:91], v[90:91], v[128:129] op_sel_hi:[1,0]
	v_pk_fma_f32 v[90:91], v[90:91], v[180:181], v[212:213]
	v_cvt_pk_bf16_f32 v88, v88, v89
	v_cvt_pk_bf16_f32 v89, v90, v91
	global_store_dwordx2 v[230:231], v[88:89], off offset:1024
	v_pk_mul_f32 v[92:93], v[92:93], v[128:129] op_sel_hi:[1,0]
	v_pk_fma_f32 v[92:93], v[92:93], v[182:183], v[214:215]
	v_pk_mul_f32 v[94:95], v[94:95], v[128:129] op_sel_hi:[1,0]
	v_pk_fma_f32 v[94:95], v[94:95], v[184:185], v[216:217]
	v_cvt_pk_bf16_f32 v92, v92, v93
	v_cvt_pk_bf16_f32 v93, v94, v95
	global_store_dwordx2 v[230:231], v[92:93], off offset:1536
	s_add_i32 s6, s6, s82
	s_cmp_lt_i32 s6, 0x4000
	s_cbranch_scc0 .Lnr_done
.Lnr_loop:
	s_cmp_lt_i32 s7, 0x4000
	s_cselect_b32 s10, s7, s11
	s_lshl_b32 s8, s10, 13
	s_add_u32 s8, s8, 0x1000
	s_mov_b32 s9, 0
	v_lshl_add_u64 v[248:249], v[134:135], 0, s[8:9]
	global_load_dwordx4 v[64:67], v[248:249], off offset:-4096
	global_load_dwordx4 v[68:71], v[248:249], off offset:-3072
	global_load_dwordx4 v[72:75], v[248:249], off offset:-2048
	global_load_dwordx4 v[76:79], v[248:249], off offset:-1024
	global_load_dwordx4 v[80:83], v[248:249], off
	global_load_dwordx4 v[84:87], v[248:249], off offset:1024
	global_load_dwordx4 v[88:91], v[248:249], off offset:2048
	global_load_dwordx4 v[92:95], v[248:249], off offset:3072
	s_add_i32 s7, s7, s82
	s_waitcnt vmcnt(48)
	v_pk_mul_f32 v[218:219], v[96:97], v[96:97]
	v_pk_fma_f32 v[218:219], v[98:99], v[98:99], v[218:219]
	v_pk_mul_f32 v[220:221], v[100:101], v[100:101]
	v_pk_fma_f32 v[220:221], v[102:103], v[102:103], v[220:221]
	v_pk_mul_f32 v[222:223], v[104:105], v[104:105]
	v_pk_fma_f32 v[222:223], v[106:107], v[106:107], v[222:223]
	v_pk_mul_f32 v[224:225], v[108:109], v[108:109]
	v_pk_fma_f32 v[224:225], v[110:111], v[110:111], v[224:225]
	v_pk_fma_f32 v[218:219], v[112:113], v[112:113], v[218:219]
	v_pk_fma_f32 v[218:219], v[114:115], v[114:115], v[218:219]
	v_pk_fma_f32 v[220:221], v[116:117], v[116:117], v[220:221]
	v_pk_fma_f32 v[220:221], v[118:119], v[118:119], v[220:221]
	v_pk_fma_f32 v[222:223], v[120:121], v[120:121], v[222:223]
	v_pk_fma_f32 v[222:223], v[122:123], v[122:123], v[222:223]
	v_pk_fma_f32 v[224:225], v[124:125], v[124:125], v[224:225]
	v_pk_fma_f32 v[224:225], v[126:127], v[126:127], v[224:225]
	v_pk_add_f32 v[218:219], v[218:219], v[220:221]
	v_pk_add_f32 v[222:223], v[222:223], v[224:225]
	v_pk_add_f32 v[218:219], v[218:219], v[222:223]
	v_add_f32_e32 v128, v218, v219
	ds_bpermute_b32 v129, v140, v128
	s_waitcnt lgkmcnt(0)
	v_add_f32_e32 v128, v128, v129
	ds_bpermute_b32 v129, v141, v128
	s_waitcnt lgkmcnt(0)
; __device__ __forceinline__ unsigned cvt_pk_bf16(float lo, float hi) { unsigned r; asm volatile("v_cvt_pk_bf16_f32 %0, %1, %2" : "=v"(r) : "v"(lo), "v"(hi)); return r; }
; __device__ __forceinline__ void norm_rows(const float* src, int nrows, const float* gam, const float* sc, const float* sh, bf16_t* dst, int tid) {
;     ...
;       ss[q] = rsqrtf(wave_sum(s) * (1.0f / DM) + 1e-6f); }
; #pragma unroll
;     for (int j = 0; j < 8; ++j) {
;       const int c = 4 * (lane + 64 * j);
;       const f32x4 mul = *(const f32x4*)(gam + c) * (1.0f + *(const f32x4*)(sc + c)); const f32x4 add = *(const f32x4*)(sh + c);
; #pragma unroll
;       for (int q = 0; q < 4; ++q) if (ok[q]) {
;         const f32x4 h = v[q][j] * ss[q] * mul + add; u32x2 w; w.x = cvt_pk_bf16(h[0], h[1]); w.y = cvt_pk_bf16(h[2], h[3]);
;         ((u32x2*)(dst + (size_t)rr[q] * DM) + lane)[64 * j] = w;
;       }
	v_add_f32_e32 v128, v128, v129
	ds_bpermute_b32 v129, v142, v128
	s_waitcnt lgkmcnt(0)
	v_add_f32_e32 v128, v128, v129
	ds_bpermute_b32 v129, v150, v128
	s_waitcnt lgkmcnt(0)
	v_add_f32_e32 v128, v128, v129
	ds_bpermute_b32 v129, v151, v128
	s_waitcnt lgkmcnt(0)
	v_add_f32_e32 v128, v128, v129
	ds_bpermute_b32 v129, v152, v128
	s_waitcnt lgkmcnt(0)
	v_add_f32_e32 v128, v128, v129
	v_fmamk_f32 v128, v128, 0x3a000000, v228
	v_mul_f32_e32 v129, 0x4b800000, v128
	v_cmp_gt_f32_e32 vcc, s67, v128
	s_nop 1
	v_cndmask_b32_e32 v128, v128, v129, vcc
	v_rsq_f32_e32 v128, v128
	s_nop 0
	v_mul_f32_e32 v129, 0x45800000, v128
	v_cndmask_b32_e32 v128, v128, v129, vcc
	s_lshl_b32 s8, s6, 12
	s_add_u32 s8, s8, 0x800
	s_mov_b32 s9, 0
	v_lshl_add_u64 v[230:231], v[136:137], 0, s[8:9]
	v_pk_mul_f32 v[96:97], v[96:97], v[128:129] op_sel_hi:[1,0]
	v_pk_fma_f32 v[96:97], v[96:97], v[154:155], v[186:187]
	v_pk_mul_f32 v[98:99], v[98:99], v[128:129] op_sel_hi:[1,0]
	v_pk_fma_f32 v[98:99], v[98:99], v[156:157], v[188:189]
	v_cvt_pk_bf16_f32 v96, v96, v97
	v_cvt_pk_bf16_f32 v97, v98, v99
	global_store_dwordx2 v[230:231], v[96:97], off offset:-2048
	v_pk_mul_f32 v[100:101], v[100:101], v[128:129] op_sel_hi:[1,0]
	v_pk_fma_f32 v[100:101], v[100:101], v[158:159], v[190:191]
	v_pk_mul_f32 v[102:103], v[102:103], v[128:129] op_sel_hi:[1,0]
	v_pk_fma_f32 v[102:103], v[102:103], v[160:161], v[192:193]
	v_cvt_pk_bf16_f32 v100, v100, v101
	v_cvt_pk_bf16_f32 v101, v102, v103
	global_store_dwordx2 v[230:231], v[100:101], off offset:-1536
	v_pk_mul_f32 v[104:105], v[104:105], v[128:129] op_sel_hi:[1,0]
	v_pk_fma_f32 v[104:105], v[104:105], v[162:163], v[194:195]
	v_pk_mul_f32 v[106:107], v[106:107], v[128:129] op_sel_hi:[1,0]
	v_pk_fma_f32 v[106:107], v[106:107], v[164:165], v[196:197]
	v_cvt_pk_bf16_f32 v104, v104, v105
	v_cvt_pk_bf16_f32 v105, v106, v107
	global_store_dwordx2 v[230:231], v[104:105], off offset:-1024
	v_pk_mul_f32 v[108:109], v[108:109], v[128:129] op_sel_hi:[1,0]
	v_pk_fma_f32 v[108:109], v[108:109], v[166:167], v[198:199]
	v_pk_mul_f32 v[110:111], v[110:111], v[128:129] op_sel_hi:[1,0]
	v_pk_fma_f32 v[110:111], v[110:111], v[168:169], v[200:201]
	v_cvt_pk_bf16_f32 v108, v108, v109
	v_cvt_pk_bf16_f32 v109, v110, v111
	global_store_dwordx2 v[230:231], v[108:109], off offset:-512
	v_pk_mul_f32 v[112:113], v[112:113], v[128:129] op_sel_hi:[1,0]
	v_pk_fma_f32 v[112:113], v[112:113], v[170:171], v[202:203]
	v_pk_mul_f32 v[114:115], v[114:115], v[128:129] op_sel_hi:[1,0]
	v_pk_fma_f32 v[114:115], v[114:115], v[172:173], v[204:205]
	v_cvt_pk_bf16_f32 v112, v112, v113
	v_cvt_pk_bf16_f32 v113, v114, v115
	global_store_dwordx2 v[230:231], v[112:113], off
	v_pk_mul_f32 v[116:117], v[116:117], v[128:129] op_sel_hi:[1,0]
	v_pk_fma_f32 v[116:117], v[116:117], v[174:175], v[206:207]
	v_pk_mul_f32 v[118:119], v[118:119], v[128:129] op_sel_hi:[1,0]
	v_pk_fma_f32 v[118:119], v[118:119], v[176:177], v[208:209]
	v_cvt_pk_bf16_f32 v116, v116, v117
	v_cvt_pk_bf16_f32 v117, v118, v119
	global_store_dwordx2 v[230:231], v[116:117], off offset:512
	v_pk_mul_f32 v[120:121], v[120:121], v[128:129] op_sel_hi:[1,0]
	v_pk_fma_f32 v[120:121], v[120:121], v[178:179], v[210:211]
	v_pk_mul_f32 v[122:123], v[122:123], v[128:129] op_sel_hi:[1,0]
	v_pk_fma_f32 v[122:123], v[122:123], v[180:181], v[212:213]
	v_cvt_pk_bf16_f32 v120, v120, v121
	v_cvt_pk_bf16_f32 v121, v122, v123
	global_store_dwordx2 v[230:231], v[120:121], off offset:1024
	v_pk_mul_f32 v[124:125], v[124:125], v[128:129] op_sel_hi:[1,0]
	v_pk_fma_f32 v[124:125], v[124:125], v[182:183], v[214:215]
	v_pk_mul_f32 v[126:127], v[126:127], v[128:129] op_sel_hi:[1,0]
	v_pk_fma_f32 v[126:127], v[126:127], v[184:185], v[216:217]
	v_cvt_pk_bf16_f32 v124, v124, v125
	v_cvt_pk_bf16_f32 v125, v126, v127
	global_store_dwordx2 v[230:231], v[124:125], off offset:1536
	s_add_i32 s6, s6, s82
	s_cmp_lt_i32 s6, 0x4000
	s_cbranch_scc0 .Lnr_done
	s_cmp_lt_i32 s7, 0x4000
	s_cselect_b32 s10, s7, s11
	s_lshl_b32 s8, s10, 13
	s_add_u32 s8, s8, 0x1000
	s_mov_b32 s9, 0
	v_lshl_add_u64 v[250:251], v[134:135], 0, s[8:9]
	global_load_dwordx4 v[96:99], v[250:251], off offset:-4096
	global_load_dwordx4 v[100:103], v[250:251], off offset:-3072
	global_load_dwordx4 v[104:107], v[250:251], off offset:-2048
	global_load_dwordx4 v[108:111], v[250:251], off offset:-1024
	global_load_dwordx4 v[112:115], v[250:251], off
	global_load_dwordx4 v[116:119], v[250:251], off offset:1024
	global_load_dwordx4 v[120:123], v[250:251], off offset:2048
	global_load_dwordx4 v[124:127], v[250:251], off offset:3072
	s_add_i32 s7, s7, s82
	s_waitcnt vmcnt(48)
	v_pk_mul_f32 v[218:219], v[0:1], v[0:1]
	v_pk_fma_f32 v[218:219], v[2:3], v[2:3], v[218:219]
	v_pk_mul_f32 v[220:221], v[4:5], v[4:5]
	v_pk_fma_f32 v[220:221], v[6:7], v[6:7], v[220:221]
	v_pk_mul_f32 v[222:223], v[8:9], v[8:9]
	v_pk_fma_f32 v[222:223], v[10:11], v[10:11], v[222:223]
	v_pk_mul_f32 v[224:225], v[12:13], v[12:13]
	v_pk_fma_f32 v[224:225], v[14:15], v[14:15], v[224:225]
	v_pk_fma_f32 v[218:219], v[16:17], v[16:17], v[218:219]
	v_pk_fma_f32 v[218:219], v[18:19], v[18:19], v[218:219]
	v_pk_fma_f32 v[220:221], v[20:21], v[20:21], v[220:221]
	v_pk_fma_f32 v[220:221], v[22:23], v[22:23], v[220:221]
	v_pk_fma_f32 v[222:223], v[24:25], v[24:25], v[222:223]
	v_pk_fma_f32 v[222:223], v[26:27], v[26:27], v[222:223]
	v_pk_fma_f32 v[224:225], v[28:29], v[28:29], v[224:225]
	v_pk_fma_f32 v[224:225], v[30:31], v[30:31], v[224:225]
	v_pk_add_f32 v[218:219], v[218:219], v[220:221]
	v_pk_add_f32 v[222:223], v[222:223], v[224:225]
	v_pk_add_f32 v[218:219], v[218:219], v[222:223]
	v_add_f32_e32 v128, v218, v219
	ds_bpermute_b32 v129, v140, v128
	s_waitcnt lgkmcnt(0)
; __device__ __forceinline__ unsigned cvt_pk_bf16(float lo, float hi) { unsigned r; asm volatile("v_cvt_pk_bf16_f32 %0, %1, %2" : "=v"(r) : "v"(lo), "v"(hi)); return r; }
; __device__ __forceinline__ void norm_rows(const float* src, int nrows, const float* gam, const float* sc, const float* sh, bf16_t* dst, int tid) {
;     ...
;       ss[q] = rsqrtf(wave_sum(s) * (1.0f / DM) + 1e-6f); }
; #pragma unroll
;     for (int j = 0; j < 8; ++j) {
;       const int c = 4 * (lane + 64 * j);
;       const f32x4 mul = *(const f32x4*)(gam + c) * (1.0f + *(const f32x4*)(sc + c)); const f32x4 add = *(const f32x4*)(sh + c);
; #pragma unroll
;       for (int q = 0; q < 4; ++q) if (ok[q]) {
;         const f32x4 h = v[q][j] * ss[q] * mul + add; u32x2 w; w.x = cvt_pk_bf16(h[0], h[1]); w.y = cvt_pk_bf16(h[2], h[3]);
;         ((u32x2*)(dst + (size_t)rr[q] * DM) + lane)[64 * j] = w;
;       }
	v_add_f32_e32 v128, v128, v129
	ds_bpermute_b32 v129, v141, v128
	s_waitcnt lgkmcnt(0)
	v_add_f32_e32 v128, v128, v129
	ds_bpermute_b32 v129, v142, v128
	s_waitcnt lgkmcnt(0)
	v_add_f32_e32 v128, v128, v129
	ds_bpermute_b32 v129, v150, v128
	s_waitcnt lgkmcnt(0)
	v_add_f32_e32 v128, v128, v129
	ds_bpermute_b32 v129, v151, v128
	s_waitcnt lgkmcnt(0)
	v_add_f32_e32 v128, v128, v129
	ds_bpermute_b32 v129, v152, v128
	s_waitcnt lgkmcnt(0)
	v_add_f32_e32 v128, v128, v129
	v_fmamk_f32 v128, v128, 0x3a000000, v228
	v_mul_f32_e32 v129, 0x4b800000, v128
	v_cmp_gt_f32_e32 vcc, s67, v128
	s_nop 1
	v_cndmask_b32_e32 v128, v128, v129, vcc
	v_rsq_f32_e32 v128, v128
	s_nop 0
	v_mul_f32_e32 v129, 0x45800000, v128
	v_cndmask_b32_e32 v128, v128, v129, vcc
	s_lshl_b32 s8, s6, 12
	s_add_u32 s8, s8, 0x800
	s_mov_b32 s9, 0
	v_lshl_add_u64 v[230:231], v[136:137], 0, s[8:9]
	v_pk_mul_f32 v[0:1], v[0:1], v[128:129] op_sel_hi:[1,0]
	v_pk_fma_f32 v[0:1], v[0:1], v[154:155], v[186:187]
	v_pk_mul_f32 v[2:3], v[2:3], v[128:129] op_sel_hi:[1,0]
	v_pk_fma_f32 v[2:3], v[2:3], v[156:157], v[188:189]
	v_cvt_pk_bf16_f32 v0, v0, v1
	v_cvt_pk_bf16_f32 v1, v2, v3
	global_store_dwordx2 v[230:231], v[0:1], off offset:-2048
	v_pk_mul_f32 v[4:5], v[4:5], v[128:129] op_sel_hi:[1,0]
	v_pk_fma_f32 v[4:5], v[4:5], v[158:159], v[190:191]
	v_pk_mul_f32 v[6:7], v[6:7], v[128:129] op_sel_hi:[1,0]
	v_pk_fma_f32 v[6:7], v[6:7], v[160:161], v[192:193]
	v_cvt_pk_bf16_f32 v4, v4, v5
	v_cvt_pk_bf16_f32 v5, v6, v7
	global_store_dwordx2 v[230:231], v[4:5], off offset:-1536
	v_pk_mul_f32 v[8:9], v[8:9], v[128:129] op_sel_hi:[1,0]
	v_pk_fma_f32 v[8:9], v[8:9], v[162:163], v[194:195]
	v_pk_mul_f32 v[10:11], v[10:11], v[128:129] op_sel_hi:[1,0]
	v_pk_fma_f32 v[10:11], v[10:11], v[164:165], v[196:197]
	v_cvt_pk_bf16_f32 v8, v8, v9
	v_cvt_pk_bf16_f32 v9, v10, v11
	global_store_dwordx2 v[230:231], v[8:9], off offset:-1024
	v_pk_mul_f32 v[12:13], v[12:13], v[128:129] op_sel_hi:[1,0]
	v_pk_fma_f32 v[12:13], v[12:13], v[166:167], v[198:199]
	v_pk_mul_f32 v[14:15], v[14:15], v[128:129] op_sel_hi:[1,0]
	v_pk_fma_f32 v[14:15], v[14:15], v[168:169], v[200:201]
	v_cvt_pk_bf16_f32 v12, v12, v13
	v_cvt_pk_bf16_f32 v13, v14, v15
	global_store_dwordx2 v[230:231], v[12:13], off offset:-512
	v_pk_mul_f32 v[16:17], v[16:17], v[128:129] op_sel_hi:[1,0]
	v_pk_fma_f32 v[16:17], v[16:17], v[170:171], v[202:203]
	v_pk_mul_f32 v[18:19], v[18:19], v[128:129] op_sel_hi:[1,0]
	v_pk_fma_f32 v[18:19], v[18:19], v[172:173], v[204:205]
	v_cvt_pk_bf16_f32 v16, v16, v17
	v_cvt_pk_bf16_f32 v17, v18, v19
	global_store_dwordx2 v[230:231], v[16:17], off
	v_pk_mul_f32 v[20:21], v[20:21], v[128:129] op_sel_hi:[1,0]
	v_pk_fma_f32 v[20:21], v[20:21], v[174:175], v[206:207]
	v_pk_mul_f32 v[22:23], v[22:23], v[128:129] op_sel_hi:[1,0]
	v_pk_fma_f32 v[22:23], v[22:23], v[176:177], v[208:209]
	v_cvt_pk_bf16_f32 v20, v20, v21
	v_cvt_pk_bf16_f32 v21, v22, v23
	global_store_dwordx2 v[230:231], v[20:21], off offset:512
	v_pk_mul_f32 v[24:25], v[24:25], v[128:129] op_sel_hi:[1,0]
	v_pk_fma_f32 v[24:25], v[24:25], v[178:179], v[210:211]
	v_pk_mul_f32 v[26:27], v[26:27], v[128:129] op_sel_hi:[1,0]
	v_pk_fma_f32 v[26:27], v[26:27], v[180:181], v[212:213]
	v_cvt_pk_bf16_f32 v24, v24, v25
	v_cvt_pk_bf16_f32 v25, v26, v27
	global_store_dwordx2 v[230:231], v[24:25], off offset:1024
	v_pk_mul_f32 v[28:29], v[28:29], v[128:129] op_sel_hi:[1,0]
	v_pk_fma_f32 v[28:29], v[28:29], v[182:183], v[214:215]
	v_pk_mul_f32 v[30:31], v[30:31], v[128:129] op_sel_hi:[1,0]
	v_pk_fma_f32 v[30:31], v[30:31], v[184:185], v[216:217]
	v_cvt_pk_bf16_f32 v28, v28, v29
	v_cvt_pk_bf16_f32 v29, v30, v31
	global_store_dwordx2 v[230:231], v[28:29], off offset:1536
	s_add_i32 s6, s6, s82
	s_cmp_lt_i32 s6, 0x4000
	s_cbranch_scc0 .Lnr_done
	s_cmp_lt_i32 s7, 0x4000
	s_cselect_b32 s10, s7, s11
	s_lshl_b32 s8, s10, 13
	s_add_u32 s8, s8, 0x1000
	s_mov_b32 s9, 0
	v_lshl_add_u64 v[244:245], v[134:135], 0, s[8:9]
	global_load_dwordx4 v[0:3], v[244:245], off offset:-4096
	global_load_dwordx4 v[4:7], v[244:245], off offset:-3072
	global_load_dwordx4 v[8:11], v[244:245], off offset:-2048
	global_load_dwordx4 v[12:15], v[244:245], off offset:-1024
	global_load_dwordx4 v[16:19], v[244:245], off
	global_load_dwordx4 v[20:23], v[244:245], off offset:1024
	global_load_dwordx4 v[24:27], v[244:245], off offset:2048
	global_load_dwordx4 v[28:31], v[244:245], off offset:3072
	s_add_i32 s7, s7, s82
	s_waitcnt vmcnt(48)
	v_pk_mul_f32 v[218:219], v[32:33], v[32:33]
	v_pk_fma_f32 v[218:219], v[34:35], v[34:35], v[218:219]
	v_pk_mul_f32 v[220:221], v[36:37], v[36:37]
	v_pk_fma_f32 v[220:221], v[38:39], v[38:39], v[220:221]
	v_pk_mul_f32 v[222:223], v[40:41], v[40:41]
	v_pk_fma_f32 v[222:223], v[42:43], v[42:43], v[222:223]
	v_pk_mul_f32 v[224:225], v[44:45], v[44:45]
	v_pk_fma_f32 v[224:225], v[46:47], v[46:47], v[224:225]
	v_pk_fma_f32 v[218:219], v[48:49], v[48:49], v[218:219]
	v_pk_fma_f32 v[218:219], v[50:51], v[50:51], v[218:219]
	v_pk_fma_f32 v[220:221], v[52:53], v[52:53], v[220:221]
	v_pk_fma_f32 v[220:221], v[54:55], v[54:55], v[220:221]
	v_pk_fma_f32 v[222:223], v[56:57], v[56:57], v[222:223]
	v_pk_fma_f32 v[222:223], v[58:59], v[58:59], v[222:223]
	v_pk_fma_f32 v[224:225], v[60:61], v[60:61], v[224:225]
	v_pk_fma_f32 v[224:225], v[62:63], v[62:63], v[224:225]
	v_pk_add_f32 v[218:219], v[218:219], v[220:221]
	v_pk_add_f32 v[222:223], v[222:223], v[224:225]
	v_pk_add_f32 v[218:219], v[218:219], v[222:223]
	v_add_f32_e32 v128, v218, v219
	ds_bpermute_b32 v129, v140, v128
	s_waitcnt lgkmcnt(0)
	v_add_f32_e32 v128, v128, v129
	ds_bpermute_b32 v129, v141, v128
	s_waitcnt lgkmcnt(0)
; __device__ __forceinline__ unsigned cvt_pk_bf16(float lo, float hi) { unsigned r; asm volatile("v_cvt_pk_bf16_f32 %0, %1, %2" : "=v"(r) : "v"(lo), "v"(hi)); return r; }
; __device__ __forceinline__ void norm_rows(const float* src, int nrows, const float* gam, const float* sc, const float* sh, bf16_t* dst, int tid) {
;     ...
;       ss[q] = rsqrtf(wave_sum(s) * (1.0f / DM) + 1e-6f); }
; #pragma unroll
;     for (int j = 0; j < 8; ++j) {
;       const int c = 4 * (lane + 64 * j);
;       const f32x4 mul = *(const f32x4*)(gam + c) * (1.0f + *(const f32x4*)(sc + c)); const f32x4 add = *(const f32x4*)(sh + c);
; #pragma unroll
;       for (int q = 0; q < 4; ++q) if (ok[q]) {
;         const f32x4 h = v[q][j] * ss[q] * mul + add; u32x2 w; w.x = cvt_pk_bf16(h[0], h[1]); w.y = cvt_pk_bf16(h[2], h[3]);
;         ((u32x2*)(dst + (size_t)rr[q] * DM) + lane)[64 * j] = w;
;       }
	v_add_f32_e32 v128, v128, v129
	ds_bpermute_b32 v129, v142, v128
	s_waitcnt lgkmcnt(0)
	v_add_f32_e32 v128, v128, v129
	ds_bpermute_b32 v129, v150, v128
	s_waitcnt lgkmcnt(0)
	v_add_f32_e32 v128, v128, v129
	ds_bpermute_b32 v129, v151, v128
	s_waitcnt lgkmcnt(0)
	v_add_f32_e32 v128, v128, v129
	ds_bpermute_b32 v129, v152, v128
	s_waitcnt lgkmcnt(0)
	v_add_f32_e32 v128, v128, v129
	v_fmamk_f32 v128, v128, 0x3a000000, v228
	v_mul_f32_e32 v129, 0x4b800000, v128
	v_cmp_gt_f32_e32 vcc, s67, v128
	s_nop 1
	v_cndmask_b32_e32 v128, v128, v129, vcc
	v_rsq_f32_e32 v128, v128
	s_nop 0
	v_mul_f32_e32 v129, 0x45800000, v128
	v_cndmask_b32_e32 v128, v128, v129, vcc
	s_lshl_b32 s8, s6, 12
	s_add_u32 s8, s8, 0x800
	s_mov_b32 s9, 0
	v_lshl_add_u64 v[230:231], v[136:137], 0, s[8:9]
	v_pk_mul_f32 v[32:33], v[32:33], v[128:129] op_sel_hi:[1,0]
	v_pk_fma_f32 v[32:33], v[32:33], v[154:155], v[186:187]
	v_pk_mul_f32 v[34:35], v[34:35], v[128:129] op_sel_hi:[1,0]
	v_pk_fma_f32 v[34:35], v[34:35], v[156:157], v[188:189]
	v_cvt_pk_bf16_f32 v32, v32, v33
	v_cvt_pk_bf16_f32 v33, v34, v35
	global_store_dwordx2 v[230:231], v[32:33], off offset:-2048
	v_pk_mul_f32 v[36:37], v[36:37], v[128:129] op_sel_hi:[1,0]
	v_pk_fma_f32 v[36:37], v[36:37], v[158:159], v[190:191]
	v_pk_mul_f32 v[38:39], v[38:39], v[128:129] op_sel_hi:[1,0]
	v_pk_fma_f32 v[38:39], v[38:39], v[160:161], v[192:193]
	v_cvt_pk_bf16_f32 v36, v36, v37
	v_cvt_pk_bf16_f32 v37, v38, v39
	global_store_dwordx2 v[230:231], v[36:37], off offset:-1536
	v_pk_mul_f32 v[40:41], v[40:41], v[128:129] op_sel_hi:[1,0]
	v_pk_fma_f32 v[40:41], v[40:41], v[162:163], v[194:195]
	v_pk_mul_f32 v[42:43], v[42:43], v[128:129] op_sel_hi:[1,0]
	v_pk_fma_f32 v[42:43], v[42:43], v[164:165], v[196:197]
	v_cvt_pk_bf16_f32 v40, v40, v41
	v_cvt_pk_bf16_f32 v41, v42, v43
	global_store_dwordx2 v[230:231], v[40:41], off offset:-1024
	v_pk_mul_f32 v[44:45], v[44:45], v[128:129] op_sel_hi:[1,0]
	v_pk_fma_f32 v[44:45], v[44:45], v[166:167], v[198:199]
	v_pk_mul_f32 v[46:47], v[46:47], v[128:129] op_sel_hi:[1,0]
	v_pk_fma_f32 v[46:47], v[46:47], v[168:169], v[200:201]
	v_cvt_pk_bf16_f32 v44, v44, v45
	v_cvt_pk_bf16_f32 v45, v46, v47
	global_store_dwordx2 v[230:231], v[44:45], off offset:-512
	v_pk_mul_f32 v[48:49], v[48:49], v[128:129] op_sel_hi:[1,0]
	v_pk_fma_f32 v[48:49], v[48:49], v[170:171], v[202:203]
	v_pk_mul_f32 v[50:51], v[50:51], v[128:129] op_sel_hi:[1,0]
	v_pk_fma_f32 v[50:51], v[50:51], v[172:173], v[204:205]
	v_cvt_pk_bf16_f32 v48, v48, v49
	v_cvt_pk_bf16_f32 v49, v50, v51
	global_store_dwordx2 v[230:231], v[48:49], off
	v_pk_mul_f32 v[52:53], v[52:53], v[128:129] op_sel_hi:[1,0]
	v_pk_fma_f32 v[52:53], v[52:53], v[174:175], v[206:207]
	v_pk_mul_f32 v[54:55], v[54:55], v[128:129] op_sel_hi:[1,0]
	v_pk_fma_f32 v[54:55], v[54:55], v[176:177], v[208:209]
	v_cvt_pk_bf16_f32 v52, v52, v53
	v_cvt_pk_bf16_f32 v53, v54, v55
	global_store_dwordx2 v[230:231], v[52:53], off offset:512
	v_pk_mul_f32 v[56:57], v[56:57], v[128:129] op_sel_hi:[1,0]
	v_pk_fma_f32 v[56:57], v[56:57], v[178:179], v[210:211]
	v_pk_mul_f32 v[58:59], v[58:59], v[128:129] op_sel_hi:[1,0]
	v_pk_fma_f32 v[58:59], v[58:59], v[180:181], v[212:213]
	v_cvt_pk_bf16_f32 v56, v56, v57
	v_cvt_pk_bf16_f32 v57, v58, v59
	global_store_dwordx2 v[230:231], v[56:57], off offset:1024
	v_pk_mul_f32 v[60:61], v[60:61], v[128:129] op_sel_hi:[1,0]
	v_pk_fma_f32 v[60:61], v[60:61], v[182:183], v[214:215]
	v_pk_mul_f32 v[62:63], v[62:63], v[128:129] op_sel_hi:[1,0]
	v_pk_fma_f32 v[62:63], v[62:63], v[184:185], v[216:217]
	v_cvt_pk_bf16_f32 v60, v60, v61
	v_cvt_pk_bf16_f32 v61, v62, v63
	global_store_dwordx2 v[230:231], v[60:61], off offset:1536
	s_add_i32 s6, s6, s82
	s_cmp_lt_i32 s6, 0x4000
	s_cbranch_scc0 .Lnr_done
	s_cmp_lt_i32 s7, 0x4000
	s_cselect_b32 s10, s7, s11
	s_lshl_b32 s8, s10, 13
	s_add_u32 s8, s8, 0x1000
	s_mov_b32 s9, 0
	v_lshl_add_u64 v[246:247], v[134:135], 0, s[8:9]
	global_load_dwordx4 v[32:35], v[246:247], off offset:-4096
	global_load_dwordx4 v[36:39], v[246:247], off offset:-3072
	global_load_dwordx4 v[40:43], v[246:247], off offset:-2048
	global_load_dwordx4 v[44:47], v[246:247], off offset:-1024
	global_load_dwordx4 v[48:51], v[246:247], off
	global_load_dwordx4 v[52:55], v[246:247], off offset:1024
	global_load_dwordx4 v[56:59], v[246:247], off offset:2048
	global_load_dwordx4 v[60:63], v[246:247], off offset:3072
	s_add_i32 s7, s7, s82
	s_waitcnt vmcnt(48)
	v_pk_mul_f32 v[218:219], v[64:65], v[64:65]
	v_pk_fma_f32 v[218:219], v[66:67], v[66:67], v[218:219]
	v_pk_mul_f32 v[220:221], v[68:69], v[68:69]
	v_pk_fma_f32 v[220:221], v[70:71], v[70:71], v[220:221]
	v_pk_mul_f32 v[222:223], v[72:73], v[72:73]
	v_pk_fma_f32 v[222:223], v[74:75], v[74:75], v[222:223]
	v_pk_mul_f32 v[224:225], v[76:77], v[76:77]
	v_pk_fma_f32 v[224:225], v[78:79], v[78:79], v[224:225]
	v_pk_fma_f32 v[218:219], v[80:81], v[80:81], v[218:219]
	v_pk_fma_f32 v[218:219], v[82:83], v[82:83], v[218:219]
	v_pk_fma_f32 v[220:221], v[84:85], v[84:85], v[220:221]
	v_pk_fma_f32 v[220:221], v[86:87], v[86:87], v[220:221]
	v_pk_fma_f32 v[222:223], v[88:89], v[88:89], v[222:223]
	v_pk_fma_f32 v[222:223], v[90:91], v[90:91], v[222:223]
	v_pk_fma_f32 v[224:225], v[92:93], v[92:93], v[224:225]
	v_pk_fma_f32 v[224:225], v[94:95], v[94:95], v[224:225]
	v_pk_add_f32 v[218:219], v[218:219], v[220:221]
	v_pk_add_f32 v[222:223], v[222:223], v[224:225]
	v_pk_add_f32 v[218:219], v[218:219], v[222:223]
	v_add_f32_e32 v128, v218, v219
	ds_bpermute_b32 v129, v140, v128
	s_waitcnt lgkmcnt(0)
	v_add_f32_e32 v128, v128, v129
	ds_bpermute_b32 v129, v141, v128
	s_waitcnt lgkmcnt(0)
; __device__ __forceinline__ unsigned cvt_pk_bf16(float lo, float hi) { unsigned r; asm volatile("v_cvt_pk_bf16_f32 %0, %1, %2" : "=v"(r) : "v"(lo), "v"(hi)); return r; }
; __device__ __forceinline__ void norm_rows(const float* src, int nrows, const float* gam, const float* sc, const float* sh, bf16_t* dst, int tid) {
;     ...
;   for (int r0 = gw; r0 < nrows; r0 += 4 * nw) {
;     f32x4 v[4][8]; float ss[4]; int rr[4]; bool ok[4];
; #pragma unroll
;     for (int q = 0; q < 4; ++q) { const int r = r0 + q * nw; ok[q] = r < nrows; rr[q] = ok[q] ? r : r0; }
; #pragma unroll
;     for (int q = 0; q < 4; ++q) { const f32x4* xr = (const f32x4*)(src + (size_t)rr[q] * DM) + lane;
; #pragma unroll
;       for (int j = 0; j < 8; ++j) v[q][j] = xr[64 * j]; }
; #pragma unroll
;     for (int q = 0; q < 4; ++q) { float s = 0.f;
; #pragma unroll
;       for (int j = 0; j < 8; ++j) s += v[q][j][0] * v[q][j][0] + v[q][j][1] * v[q][j][1] + v[q][j][2] * v[q][j][2] + v[q][j][3] * v[q][j][3];
;       ss[q] = rsqrtf(wave_sum(s) * (1.0f / DM) + 1e-6f); }
; #pragma unroll
;     for (int j = 0; j < 8; ++j) {
;       const int c = 4 * (lane + 64 * j);
;       const f32x4 mul = *(const f32x4*)(gam + c) * (1.0f + *(const f32x4*)(sc + c)); const f32x4 add = *(const f32x4*)(sh + c);
; #pragma unroll
;       for (int q = 0; q < 4; ++q) if (ok[q]) {
;         const f32x4 h = v[q][j] * ss[q] * mul + add; u32x2 w; w.x = cvt_pk_bf16(h[0], h[1]); w.y = cvt_pk_bf16(h[2], h[3]);
;         ((u32x2*)(dst + (size_t)rr[q] * DM) + lane)[64 * j] = w;
;       }
;     }
;   }
; }
; __device__ __forceinline__ void phase_norm(KP p, int ph, unsigned char* shm, int tid) {
;     ...
;   if (ph == 1) norm_rows(p->in[2], CTXL, gam, modv + 24576 + DM, modv + 24576, HA + (size_t)SEQ * DM, tid);
	v_add_f32_e32 v128, v128, v129
	ds_bpermute_b32 v129, v142, v128
	s_waitcnt lgkmcnt(0)
	v_add_f32_e32 v128, v128, v129
	ds_bpermute_b32 v129, v150, v128
	s_waitcnt lgkmcnt(0)
	v_add_f32_e32 v128, v128, v129
	ds_bpermute_b32 v129, v151, v128
	s_waitcnt lgkmcnt(0)
	v_add_f32_e32 v128, v128, v129
	ds_bpermute_b32 v129, v152, v128
	s_waitcnt lgkmcnt(0)
	v_add_f32_e32 v128, v128, v129
	v_fmamk_f32 v128, v128, 0x3a000000, v228
	v_mul_f32_e32 v129, 0x4b800000, v128
	v_cmp_gt_f32_e32 vcc, s67, v128
	s_nop 1
	v_cndmask_b32_e32 v128, v128, v129, vcc
	v_rsq_f32_e32 v128, v128
	s_nop 0
	v_mul_f32_e32 v129, 0x45800000, v128
	v_cndmask_b32_e32 v128, v128, v129, vcc
	s_lshl_b32 s8, s6, 12
	s_add_u32 s8, s8, 0x800
	s_mov_b32 s9, 0
	v_lshl_add_u64 v[230:231], v[136:137], 0, s[8:9]
	v_pk_mul_f32 v[64:65], v[64:65], v[128:129] op_sel_hi:[1,0]
	v_pk_fma_f32 v[64:65], v[64:65], v[154:155], v[186:187]
	v_pk_mul_f32 v[66:67], v[66:67], v[128:129] op_sel_hi:[1,0]
	v_pk_fma_f32 v[66:67], v[66:67], v[156:157], v[188:189]
	v_cvt_pk_bf16_f32 v64, v64, v65
	v_cvt_pk_bf16_f32 v65, v66, v67
	global_store_dwordx2 v[230:231], v[64:65], off offset:-2048
	v_pk_mul_f32 v[68:69], v[68:69], v[128:129] op_sel_hi:[1,0]
	v_pk_fma_f32 v[68:69], v[68:69], v[158:159], v[190:191]
	v_pk_mul_f32 v[70:71], v[70:71], v[128:129] op_sel_hi:[1,0]
	v_pk_fma_f32 v[70:71], v[70:71], v[160:161], v[192:193]
	v_cvt_pk_bf16_f32 v68, v68, v69
	v_cvt_pk_bf16_f32 v69, v70, v71
	global_store_dwordx2 v[230:231], v[68:69], off offset:-1536
	v_pk_mul_f32 v[72:73], v[72:73], v[128:129] op_sel_hi:[1,0]
	v_pk_fma_f32 v[72:73], v[72:73], v[162:163], v[194:195]
	v_pk_mul_f32 v[74:75], v[74:75], v[128:129] op_sel_hi:[1,0]
	v_pk_fma_f32 v[74:75], v[74:75], v[164:165], v[196:197]
	v_cvt_pk_bf16_f32 v72, v72, v73
	v_cvt_pk_bf16_f32 v73, v74, v75
	global_store_dwordx2 v[230:231], v[72:73], off offset:-1024
	v_pk_mul_f32 v[76:77], v[76:77], v[128:129] op_sel_hi:[1,0]
	v_pk_fma_f32 v[76:77], v[76:77], v[166:167], v[198:199]
	v_pk_mul_f32 v[78:79], v[78:79], v[128:129] op_sel_hi:[1,0]
	v_pk_fma_f32 v[78:79], v[78:79], v[168:169], v[200:201]
	v_cvt_pk_bf16_f32 v76, v76, v77
	v_cvt_pk_bf16_f32 v77, v78, v79
	global_store_dwordx2 v[230:231], v[76:77], off offset:-512
	v_pk_mul_f32 v[80:81], v[80:81], v[128:129] op_sel_hi:[1,0]
	v_pk_fma_f32 v[80:81], v[80:81], v[170:171], v[202:203]
	v_pk_mul_f32 v[82:83], v[82:83], v[128:129] op_sel_hi:[1,0]
	v_pk_fma_f32 v[82:83], v[82:83], v[172:173], v[204:205]
	v_cvt_pk_bf16_f32 v80, v80, v81
	v_cvt_pk_bf16_f32 v81, v82, v83
	global_store_dwordx2 v[230:231], v[80:81], off
	v_pk_mul_f32 v[84:85], v[84:85], v[128:129] op_sel_hi:[1,0]
	v_pk_fma_f32 v[84:85], v[84:85], v[174:175], v[206:207]
	v_pk_mul_f32 v[86:87], v[86:87], v[128:129] op_sel_hi:[1,0]
	v_pk_fma_f32 v[86:87], v[86:87], v[176:177], v[208:209]
	v_cvt_pk_bf16_f32 v84, v84, v85
	v_cvt_pk_bf16_f32 v85, v86, v87
	global_store_dwordx2 v[230:231], v[84:85], off offset:512
	v_pk_mul_f32 v[88:89], v[88:89], v[128:129] op_sel_hi:[1,0]
	v_pk_fma_f32 v[88:89], v[88:89], v[178:179], v[210:211]
	v_pk_mul_f32 v[90:91], v[90:91], v[128:129] op_sel_hi:[1,0]
	v_pk_fma_f32 v[90:91], v[90:91], v[180:181], v[212:213]
	v_cvt_pk_bf16_f32 v88, v88, v89
	v_cvt_pk_bf16_f32 v89, v90, v91
	global_store_dwordx2 v[230:231], v[88:89], off offset:1024
	v_pk_mul_f32 v[92:93], v[92:93], v[128:129] op_sel_hi:[1,0]
	v_pk_fma_f32 v[92:93], v[92:93], v[182:183], v[214:215]
	v_pk_mul_f32 v[94:95], v[94:95], v[128:129] op_sel_hi:[1,0]
	v_pk_fma_f32 v[94:95], v[94:95], v[184:185], v[216:217]
	v_cvt_pk_bf16_f32 v92, v92, v93
	v_cvt_pk_bf16_f32 v93, v94, v95
	global_store_dwordx2 v[230:231], v[92:93], off offset:1536
	s_add_i32 s6, s6, s82
	s_cmp_lt_i32 s6, 0x4000
	s_cbranch_scc0 .Lnr_done
	s_branch .Lnr_loop
.Lnr_done:
	s_waitcnt vmcnt(0)
.LBB0_399:
	s_or_b64 exec, exec, s[14:15]
	v_cmp_gt_i32_e32 vcc, s88, v132
	s_and_b64 s[6:7], s[4:5], vcc
	s_and_saveexec_b64 s[4:5], s[6:7]
	s_cbranch_execz .LBB0_450
	s_add_u32 s6, s0, 0x6c1a000
	v_and_b32_e32 v0, 63, v229
	s_addc_u32 s7, s1, 0
	v_lshlrev_b32_e32 v138, 4, v0
	v_lshlrev_b32_e32 v0, 3, v0
	v_mov_b32_e32 v1, v139
	s_add_u32 s10, s0, 0x6c18000
	v_lshl_add_u64 v[2:3], s[0:1], 0, v[0:1]
	s_mov_b64 s[12:13], 0xac21000
	s_addc_u32 s11, s1, 0
	v_lshl_add_u64 v[136:137], v[2:3], 0, s[12:13]
	v_or_b32_e32 v2, 0x400, v138
	v_mov_b32_e32 v3, v139
	v_lshl_add_u64 v[154:155], s[6:7], 0, v[2:3]
	v_lshl_add_u64 v[156:157], s[10:11], 0, v[2:3]
	v_or_b32_e32 v2, 0x800, v138
	v_lshl_add_u64 v[158:159], s[6:7], 0, v[2:3]
	v_lshl_add_u64 v[160:161], s[10:11], 0, v[2:3]
	v_or_b32_e32 v2, 0xc00, v138
	v_lshl_add_u64 v[162:163], s[6:7], 0, v[2:3]
	v_lshl_add_u64 v[164:165], s[10:11], 0, v[2:3]
	v_or_b32_e32 v2, 0x1000, v138
	v_lshl_add_u64 v[166:167], s[2:3], 0, v[2:3]
	v_lshl_add_u64 v[168:169], s[6:7], 0, v[2:3]
	v_lshl_add_u64 v[170:171], s[10:11], 0, v[2:3]
	v_or_b32_e32 v2, 0x1400, v138
	v_readlane_b32 s8, v254, 9
	v_lshl_add_u64 v[172:173], s[2:3], 0, v[2:3]
	v_lshl_add_u64 v[174:175], s[6:7], 0, v[2:3]
	v_lshl_add_u64 v[176:177], s[10:11], 0, v[2:3]
	v_or_b32_e32 v2, 0x1800, v138
	v_readlane_b32 s9, v254, 10
	v_lshl_add_u64 v[178:179], s[2:3], 0, v[2:3]
	v_lshl_add_u64 v[180:181], s[6:7], 0, v[2:3]
	v_lshl_add_u64 v[182:183], s[10:11], 0, v[2:3]
	v_or_b32_e32 v2, 0x1c00, v138
	s_load_dwordx2 s[8:9], s[8:9], 0x10
	v_lshl_add_u64 v[184:185], s[2:3], 0, v[2:3]
	v_lshl_add_u64 v[186:187], s[6:7], 0, v[2:3]
	v_lshl_add_u64 v[188:189], s[10:11], 0, v[2:3]
	v_lshlrev_b64 v[2:3], 12, v[132:133]
	v_or_b32_e32 v2, v2, v0
	v_lshl_add_u64 v[148:149], s[2:3], 0, v[138:139]
	v_lshl_add_u64 v[0:1], s[0:1], 0, v[2:3]
	s_mov_b64 s[2:3], 0xac21e00
	v_lshl_add_u64 v[190:191], v[0:1], 0, s[2:3]
	v_lshlrev_b64 v[0:1], 13, v[132:133]
	v_or_b32_e32 v0, v0, v138
	s_waitcnt lgkmcnt(0)
	v_lshl_add_u64 v[0:1], s[8:9], 0, v[0:1]
	s_mov_b64 s[2:3], 0x1c00
	v_lshl_add_u64 v[134:135], s[8:9], 0, v[138:139]
	v_lshl_add_u64 v[150:151], s[6:7], 0, v[138:139]
	v_lshl_add_u64 v[152:153], s[10:11], 0, v[138:139]
	v_lshl_add_u64 v[192:193], v[0:1], 0, s[2:3]
	s_mov_b64 s[2:3], 0
	v_mov_b32_e32 v133, v132
	s_branch .LBB0_402
